# phase_norm ctx fold path: the 72 one-at-a-time partial-slab loads per row issued 18 at a time (both instances)
# baseline (speedup 1.0000x reference)
; template <class T> DI T* LP(T* p) { asm volatile("" : "+s"(p)); return p; }
; #define PRM (*KP())
; DI void phase_norm(int l, int stage, bool skipctx, int fold, int gate_l, int gate_chunk, const void* latsrc, int lat_bf16) {
;     ...
;         if (isctx && fold) {
;             const float* part = (const float*)(LP(PRM.ws) + WS_PART) + ((size_t)b * CTXL + t) * DM; const float* gt = mod + ((size_t)gate_l * 3 + 2) * 12288 + (size_t)gate_chunk * DM;
;             float* xc = (float*)(LP(PRM.ws) + WS_XC) + ((size_t)b * CTXL + t) * DM;
; #pragma unroll
;             for (int j = 0; j < 8; ++j) { f32x4 a = *((const f32x4*)part + 64 * j + lane);
; #pragma unroll
;                 for (int k = 1; k < NSPLIT; ++k) a += *((const f32x4*)(part + (size_t)k * 512 * DM) + 64 * j + lane);
;                 v[j] += a * *((const f32x4*)gt + 64 * j + lane); *((f32x4*)xc + 64 * j + lane) = v[j]; }
;         }
.LBB0_189:
	s_mov_b64 s[6:7], s[0:1]
	v_ashrrev_i32_e32 v141, 31, v140
	v_lshlrev_b64 v[138:139], 19, v[138:139]
	v_lshlrev_b64 v[140:141], 11, v[140:141]
	s_load_dwordx2 s[6:7], s[6:7], 0xa8
	v_lshl_add_u64 v[138:139], v[138:139], 0, v[140:141]
	s_waitcnt lgkmcnt(0)
	v_lshlrev_b64 v[138:139], 2, v[138:139]
	v_lshl_add_u64 v[140:141], s[6:7], 0, v[138:139]
	s_mov_b64 s[6:7], s[0:1]
	s_load_dwordx2 s[6:7], s[6:7], 0xa8
	s_waitcnt lgkmcnt(0)
	v_mov_b32_e32 v143, v177
	v_lshl_add_u64 v[138:139], s[6:7], 0, v[138:139]
	v_lshl_add_u64 v[140:141], v[140:141], 0, v[142:143]
	s_mov_b64 s[6:7], 0x26acc000
	v_lshl_add_u64 v[144:145], v[140:141], 0, s[6:7]
	v_lshl_add_u64 v[138:139], v[138:139], 0, v[142:143]
	s_mov_b64 s[6:7], 0x48000
	v_lshl_add_u64 v[142:143], v[138:139], 0, s[6:7]
	s_mov_b64 s[6:7], 0x400000
	v_lshl_add_u64 v[178:179], v[144:145], 0, s[6:7]
	v_lshl_add_u64 v[180:181], v[178:179], 0, s[6:7]
	v_lshl_add_u64 v[182:183], v[180:181], 0, s[6:7]
	v_lshl_add_u64 v[184:185], v[182:183], 0, s[6:7]
	v_lshl_add_u64 v[186:187], v[184:185], 0, s[6:7]
	v_lshl_add_u64 v[188:189], v[186:187], 0, s[6:7]
	v_lshl_add_u64 v[190:191], v[188:189], 0, s[6:7]
	s_mov_b64 s[6:7], 0x1000
	v_lshl_add_u64 v[232:233], v[142:143], 0, s[6:7]
	global_load_dwordx4 v[192:195], v[144:145], off
	global_load_dwordx4 v[196:199], v[178:179], off
	global_load_dwordx4 v[200:203], v[180:181], off
	global_load_dwordx4 v[204:207], v[182:183], off
	global_load_dwordx4 v[208:211], v[184:185], off
	global_load_dwordx4 v[212:215], v[186:187], off
	global_load_dwordx4 v[238:241], v[188:189], off
	global_load_dwordx4 v[242:245], v[190:191], off
	global_load_dwordx4 v[246:249], v[100:101], off
	global_load_dwordx4 v[148:151], v[144:145], off offset:1024
	global_load_dwordx4 v[152:155], v[178:179], off offset:1024
	global_load_dwordx4 v[156:159], v[180:181], off offset:1024
	global_load_dwordx4 v[160:163], v[182:183], off offset:1024
	global_load_dwordx4 v[164:167], v[184:185], off offset:1024
	global_load_dwordx4 v[168:171], v[186:187], off offset:1024
	global_load_dwordx4 v[172:175], v[188:189], off offset:1024
	global_load_dwordx4 v[250:253], v[190:191], off offset:1024
	global_load_dwordx4 v[228:231], v[100:101], off offset:1024
	s_waitcnt vmcnt(9)
	v_pk_add_f32 v[192:193], v[192:193], v[196:197]
	v_pk_add_f32 v[194:195], v[194:195], v[198:199]
	v_pk_add_f32 v[192:193], v[192:193], v[200:201]
	v_pk_add_f32 v[194:195], v[194:195], v[202:203]
	v_pk_add_f32 v[192:193], v[192:193], v[204:205]
	v_pk_add_f32 v[194:195], v[194:195], v[206:207]
	v_pk_add_f32 v[192:193], v[192:193], v[208:209]
	v_pk_add_f32 v[194:195], v[194:195], v[210:211]
	v_pk_add_f32 v[192:193], v[192:193], v[212:213]
	v_pk_add_f32 v[194:195], v[194:195], v[214:215]
	v_pk_add_f32 v[192:193], v[192:193], v[238:239]
	v_pk_add_f32 v[194:195], v[194:195], v[240:241]
	v_pk_add_f32 v[192:193], v[192:193], v[242:243]
	v_pk_add_f32 v[194:195], v[194:195], v[244:245]
	v_pk_fma_f32 v[92:93], v[192:193], v[246:247], v[92:93]
	v_pk_fma_f32 v[94:95], v[194:195], v[248:249], v[94:95]
	global_store_dwordx4 v[142:143], v[92:95], off
	s_waitcnt vmcnt(1)
	v_pk_add_f32 v[148:149], v[148:149], v[152:153]
	v_pk_add_f32 v[150:151], v[150:151], v[154:155]
	v_pk_add_f32 v[148:149], v[148:149], v[156:157]
	v_pk_add_f32 v[150:151], v[150:151], v[158:159]
	v_pk_add_f32 v[148:149], v[148:149], v[160:161]
	v_pk_add_f32 v[150:151], v[150:151], v[162:163]
	v_pk_add_f32 v[148:149], v[148:149], v[164:165]
	v_pk_add_f32 v[150:151], v[150:151], v[166:167]
	v_pk_add_f32 v[148:149], v[148:149], v[168:169]
	v_pk_add_f32 v[150:151], v[150:151], v[170:171]
	v_pk_add_f32 v[148:149], v[148:149], v[172:173]
	v_pk_add_f32 v[150:151], v[150:151], v[174:175]
	v_pk_add_f32 v[148:149], v[148:149], v[250:251]
	v_pk_add_f32 v[150:151], v[150:151], v[252:253]
	v_pk_fma_f32 v[88:89], v[148:149], v[228:229], v[88:89]
	v_pk_fma_f32 v[90:91], v[150:151], v[230:231], v[90:91]
	global_store_dwordx4 v[142:143], v[88:91], off offset:1024
	global_load_dwordx4 v[192:195], v[144:145], off offset:2048
	global_load_dwordx4 v[196:199], v[178:179], off offset:2048
	global_load_dwordx4 v[200:203], v[180:181], off offset:2048
	global_load_dwordx4 v[204:207], v[182:183], off offset:2048
	global_load_dwordx4 v[208:211], v[184:185], off offset:2048
	global_load_dwordx4 v[212:215], v[186:187], off offset:2048
	global_load_dwordx4 v[238:241], v[188:189], off offset:2048
	global_load_dwordx4 v[242:245], v[190:191], off offset:2048
	global_load_dwordx4 v[246:249], v[100:101], off offset:2048
	global_load_dwordx4 v[148:151], v[144:145], off offset:3072
	global_load_dwordx4 v[152:155], v[178:179], off offset:3072
	global_load_dwordx4 v[156:159], v[180:181], off offset:3072
	global_load_dwordx4 v[160:163], v[182:183], off offset:3072
	global_load_dwordx4 v[164:167], v[184:185], off offset:3072
	global_load_dwordx4 v[168:171], v[186:187], off offset:3072
	global_load_dwordx4 v[172:175], v[188:189], off offset:3072
	global_load_dwordx4 v[250:253], v[190:191], off offset:3072
	global_load_dwordx4 v[228:231], v[100:101], off offset:3072
	s_waitcnt vmcnt(9)
	v_pk_add_f32 v[192:193], v[192:193], v[196:197]
	v_pk_add_f32 v[194:195], v[194:195], v[198:199]
	v_pk_add_f32 v[192:193], v[192:193], v[200:201]
	v_pk_add_f32 v[194:195], v[194:195], v[202:203]
	v_pk_add_f32 v[192:193], v[192:193], v[204:205]
	v_pk_add_f32 v[194:195], v[194:195], v[206:207]
	v_pk_add_f32 v[192:193], v[192:193], v[208:209]
	v_pk_add_f32 v[194:195], v[194:195], v[210:211]
	v_pk_add_f32 v[192:193], v[192:193], v[212:213]
	v_pk_add_f32 v[194:195], v[194:195], v[214:215]
	v_pk_add_f32 v[192:193], v[192:193], v[238:239]
	v_pk_add_f32 v[194:195], v[194:195], v[240:241]
	v_pk_add_f32 v[192:193], v[192:193], v[242:243]
	v_pk_add_f32 v[194:195], v[194:195], v[244:245]
	v_pk_fma_f32 v[84:85], v[192:193], v[246:247], v[84:85]
	v_pk_fma_f32 v[86:87], v[194:195], v[248:249], v[86:87]
	global_store_dwordx4 v[142:143], v[84:87], off offset:2048
	s_waitcnt vmcnt(1)
; template <class T> DI T* LP(T* p) { asm volatile("" : "+s"(p)); return p; }
; #define PRM (*KP())
; DI void phase_norm(int l, int stage, bool skipctx, int fold, int gate_l, int gate_chunk, const void* latsrc, int lat_bf16) {
;     ...
;         if (isctx && fold) {
;             const float* part = (const float*)(LP(PRM.ws) + WS_PART) + ((size_t)b * CTXL + t) * DM; const float* gt = mod + ((size_t)gate_l * 3 + 2) * 12288 + (size_t)gate_chunk * DM;
;             float* xc = (float*)(LP(PRM.ws) + WS_XC) + ((size_t)b * CTXL + t) * DM;
; #pragma unroll
;             for (int j = 0; j < 8; ++j) { f32x4 a = *((const f32x4*)part + 64 * j + lane);
; #pragma unroll
;                 for (int k = 1; k < NSPLIT; ++k) a += *((const f32x4*)(part + (size_t)k * 512 * DM) + 64 * j + lane);
;                 v[j] += a * *((const f32x4*)gt + 64 * j + lane); *((f32x4*)xc + 64 * j + lane) = v[j]; }
;         }
	v_pk_add_f32 v[148:149], v[148:149], v[152:153]
	v_pk_add_f32 v[150:151], v[150:151], v[154:155]
	v_pk_add_f32 v[148:149], v[148:149], v[156:157]
	v_pk_add_f32 v[150:151], v[150:151], v[158:159]
	v_pk_add_f32 v[148:149], v[148:149], v[160:161]
	v_pk_add_f32 v[150:151], v[150:151], v[162:163]
	v_pk_add_f32 v[148:149], v[148:149], v[164:165]
	v_pk_add_f32 v[150:151], v[150:151], v[166:167]
	v_pk_add_f32 v[148:149], v[148:149], v[168:169]
	v_pk_add_f32 v[150:151], v[150:151], v[170:171]
	v_pk_add_f32 v[148:149], v[148:149], v[172:173]
	v_pk_add_f32 v[150:151], v[150:151], v[174:175]
	v_pk_add_f32 v[148:149], v[148:149], v[250:251]
	v_pk_add_f32 v[150:151], v[150:151], v[252:253]
	v_pk_fma_f32 v[80:81], v[148:149], v[228:229], v[80:81]
	v_pk_fma_f32 v[82:83], v[150:151], v[230:231], v[82:83]
	global_store_dwordx4 v[142:143], v[80:83], off offset:3072
	v_lshl_add_u64 v[144:145], v[144:145], 0, s[6:7]
	v_lshl_add_u64 v[178:179], v[178:179], 0, s[6:7]
	v_lshl_add_u64 v[180:181], v[180:181], 0, s[6:7]
	v_lshl_add_u64 v[182:183], v[182:183], 0, s[6:7]
	v_lshl_add_u64 v[184:185], v[184:185], 0, s[6:7]
	v_lshl_add_u64 v[186:187], v[186:187], 0, s[6:7]
	v_lshl_add_u64 v[188:189], v[188:189], 0, s[6:7]
	v_lshl_add_u64 v[190:191], v[190:191], 0, s[6:7]
	global_load_dwordx4 v[192:195], v[144:145], off
	global_load_dwordx4 v[196:199], v[178:179], off
	global_load_dwordx4 v[200:203], v[180:181], off
	global_load_dwordx4 v[204:207], v[182:183], off
	global_load_dwordx4 v[208:211], v[184:185], off
	global_load_dwordx4 v[212:215], v[186:187], off
	global_load_dwordx4 v[238:241], v[188:189], off
	global_load_dwordx4 v[242:245], v[190:191], off
	global_load_dwordx4 v[246:249], v[112:113], off
	global_load_dwordx4 v[148:151], v[144:145], off offset:1024
	global_load_dwordx4 v[152:155], v[178:179], off offset:1024
	global_load_dwordx4 v[156:159], v[180:181], off offset:1024
	global_load_dwordx4 v[160:163], v[182:183], off offset:1024
	global_load_dwordx4 v[164:167], v[184:185], off offset:1024
	global_load_dwordx4 v[168:171], v[186:187], off offset:1024
	global_load_dwordx4 v[172:175], v[188:189], off offset:1024
	global_load_dwordx4 v[250:253], v[190:191], off offset:1024
	global_load_dwordx4 v[228:231], v[114:115], off
	s_waitcnt vmcnt(9)
	v_pk_add_f32 v[192:193], v[192:193], v[196:197]
	v_pk_add_f32 v[194:195], v[194:195], v[198:199]
	v_pk_add_f32 v[192:193], v[192:193], v[200:201]
	v_pk_add_f32 v[194:195], v[194:195], v[202:203]
	v_pk_add_f32 v[192:193], v[192:193], v[204:205]
	v_pk_add_f32 v[194:195], v[194:195], v[206:207]
	v_pk_add_f32 v[192:193], v[192:193], v[208:209]
	v_pk_add_f32 v[194:195], v[194:195], v[210:211]
	v_pk_add_f32 v[192:193], v[192:193], v[212:213]
	v_pk_add_f32 v[194:195], v[194:195], v[214:215]
	v_pk_add_f32 v[192:193], v[192:193], v[238:239]
	v_pk_add_f32 v[194:195], v[194:195], v[240:241]
	v_pk_add_f32 v[192:193], v[192:193], v[242:243]
	v_pk_add_f32 v[194:195], v[194:195], v[244:245]
	v_pk_fma_f32 v[76:77], v[192:193], v[246:247], v[76:77]
	v_pk_fma_f32 v[78:79], v[194:195], v[248:249], v[78:79]
	global_store_dwordx4 v[232:233], v[76:79], off
	s_waitcnt vmcnt(1)
	v_pk_add_f32 v[148:149], v[148:149], v[152:153]
	v_pk_add_f32 v[150:151], v[150:151], v[154:155]
	v_pk_add_f32 v[148:149], v[148:149], v[156:157]
	v_pk_add_f32 v[150:151], v[150:151], v[158:159]
	v_pk_add_f32 v[148:149], v[148:149], v[160:161]
	v_pk_add_f32 v[150:151], v[150:151], v[162:163]
	v_pk_add_f32 v[148:149], v[148:149], v[164:165]
	v_pk_add_f32 v[150:151], v[150:151], v[166:167]
	v_pk_add_f32 v[148:149], v[148:149], v[168:169]
	v_pk_add_f32 v[150:151], v[150:151], v[170:171]
	v_pk_add_f32 v[148:149], v[148:149], v[172:173]
	v_pk_add_f32 v[150:151], v[150:151], v[174:175]
	v_pk_add_f32 v[148:149], v[148:149], v[250:251]
	v_pk_add_f32 v[150:151], v[150:151], v[252:253]
	v_pk_fma_f32 v[72:73], v[148:149], v[228:229], v[72:73]
	v_pk_fma_f32 v[74:75], v[150:151], v[230:231], v[74:75]
	global_store_dwordx4 v[232:233], v[72:75], off offset:1024
	global_load_dwordx4 v[192:195], v[144:145], off offset:2048
	global_load_dwordx4 v[196:199], v[178:179], off offset:2048
	global_load_dwordx4 v[200:203], v[180:181], off offset:2048
	global_load_dwordx4 v[204:207], v[182:183], off offset:2048
	global_load_dwordx4 v[208:211], v[184:185], off offset:2048
	global_load_dwordx4 v[212:215], v[186:187], off offset:2048
	global_load_dwordx4 v[238:241], v[188:189], off offset:2048
	global_load_dwordx4 v[242:245], v[190:191], off offset:2048
	global_load_dwordx4 v[246:249], v[116:117], off
	global_load_dwordx4 v[148:151], v[144:145], off offset:3072
	global_load_dwordx4 v[152:155], v[178:179], off offset:3072
	global_load_dwordx4 v[156:159], v[180:181], off offset:3072
	global_load_dwordx4 v[160:163], v[182:183], off offset:3072
	global_load_dwordx4 v[164:167], v[184:185], off offset:3072
	global_load_dwordx4 v[168:171], v[186:187], off offset:3072
	global_load_dwordx4 v[172:175], v[188:189], off offset:3072
	global_load_dwordx4 v[250:253], v[190:191], off offset:3072
	global_load_dwordx4 v[228:231], v[118:119], off
	s_waitcnt vmcnt(9)
	v_pk_add_f32 v[192:193], v[192:193], v[196:197]
	v_pk_add_f32 v[194:195], v[194:195], v[198:199]
	v_pk_add_f32 v[192:193], v[192:193], v[200:201]
	v_pk_add_f32 v[194:195], v[194:195], v[202:203]
	v_pk_add_f32 v[192:193], v[192:193], v[204:205]
	v_pk_add_f32 v[194:195], v[194:195], v[206:207]
	v_pk_add_f32 v[192:193], v[192:193], v[208:209]
	v_pk_add_f32 v[194:195], v[194:195], v[210:211]
	v_pk_add_f32 v[192:193], v[192:193], v[212:213]
	v_pk_add_f32 v[194:195], v[194:195], v[214:215]
	v_pk_add_f32 v[192:193], v[192:193], v[238:239]
	v_pk_add_f32 v[194:195], v[194:195], v[240:241]
	v_pk_add_f32 v[192:193], v[192:193], v[242:243]
	v_pk_add_f32 v[194:195], v[194:195], v[244:245]
	v_pk_fma_f32 v[68:69], v[192:193], v[246:247], v[68:69]
	v_pk_fma_f32 v[70:71], v[194:195], v[248:249], v[70:71]
	global_store_dwordx4 v[232:233], v[68:71], off offset:2048
	s_waitcnt vmcnt(1)
	v_pk_add_f32 v[148:149], v[148:149], v[152:153]
	v_pk_add_f32 v[150:151], v[150:151], v[154:155]
	v_pk_add_f32 v[148:149], v[148:149], v[156:157]
	v_pk_add_f32 v[150:151], v[150:151], v[158:159]
	v_pk_add_f32 v[148:149], v[148:149], v[160:161]
	v_pk_add_f32 v[150:151], v[150:151], v[162:163]
	v_pk_add_f32 v[148:149], v[148:149], v[164:165]
	v_pk_add_f32 v[150:151], v[150:151], v[166:167]
	v_pk_add_f32 v[148:149], v[148:149], v[168:169]
	v_pk_add_f32 v[150:151], v[150:151], v[170:171]
	v_pk_add_f32 v[148:149], v[148:149], v[172:173]
	v_pk_add_f32 v[150:151], v[150:151], v[174:175]
	v_pk_add_f32 v[148:149], v[148:149], v[250:251]
	v_pk_add_f32 v[150:151], v[150:151], v[252:253]
	v_pk_fma_f32 v[64:65], v[148:149], v[228:229], v[64:65]
	v_pk_fma_f32 v[66:67], v[150:151], v[230:231], v[66:67]
	global_store_dwordx4 v[232:233], v[64:67], off offset:3072
	s_branch .LBB0_169

; template <class T> DI T* LP(T* p) { asm volatile("" : "+s"(p)); return p; }
; #define PRM (*KP())
; DI void phase_norm(int l, int stage, bool skipctx, int fold, int gate_l, int gate_chunk, const void* latsrc, int lat_bf16) {
;     ...
;         if (isctx && fold) {
;             const float* part = (const float*)(LP(PRM.ws) + WS_PART) + ((size_t)b * CTXL + t) * DM; const float* gt = mod + ((size_t)gate_l * 3 + 2) * 12288 + (size_t)gate_chunk * DM;
;             float* xc = (float*)(LP(PRM.ws) + WS_XC) + ((size_t)b * CTXL + t) * DM;
; #pragma unroll
;             for (int j = 0; j < 8; ++j) { f32x4 a = *((const f32x4*)part + 64 * j + lane);
; #pragma unroll
;                 for (int k = 1; k < NSPLIT; ++k) a += *((const f32x4*)(part + (size_t)k * 512 * DM) + 64 * j + lane);
;                 v[j] += a * *((const f32x4*)gt + 64 * j + lane); *((f32x4*)xc + 64 * j + lane) = v[j]; }
;         }
.LBB0_854:
	s_mov_b64 s[6:7], s[0:1]
	v_lshlrev_b64 v[136:137], 19, v[136:137]
	v_lshlrev_b64 v[138:139], 11, v[138:139]
	s_load_dwordx2 s[6:7], s[6:7], 0xa8
	v_lshl_add_u64 v[136:137], v[136:137], 0, v[138:139]
	s_waitcnt lgkmcnt(0)
	v_lshlrev_b64 v[136:137], 2, v[136:137]
	v_lshl_add_u64 v[138:139], s[6:7], 0, v[136:137]
	s_mov_b64 s[6:7], s[0:1]
	s_load_dwordx2 s[6:7], s[6:7], 0xa8
	s_waitcnt lgkmcnt(0)
	v_mov_b32_e32 v141, v177
	v_lshl_add_u64 v[136:137], s[6:7], 0, v[136:137]
	v_lshl_add_u64 v[138:139], v[138:139], 0, v[140:141]
	s_mov_b64 s[6:7], 0x26acc000
	v_lshl_add_u64 v[142:143], v[138:139], 0, s[6:7]
	v_lshl_add_u64 v[136:137], v[136:137], 0, v[140:141]
	s_mov_b64 s[6:7], 0x48000
	v_lshl_add_u64 v[140:141], v[136:137], 0, s[6:7]
	s_mov_b64 s[6:7], 0x400000
	v_lshl_add_u64 v[178:179], v[142:143], 0, s[6:7]
	v_lshl_add_u64 v[180:181], v[178:179], 0, s[6:7]
	v_lshl_add_u64 v[182:183], v[180:181], 0, s[6:7]
	v_lshl_add_u64 v[184:185], v[182:183], 0, s[6:7]
	v_lshl_add_u64 v[186:187], v[184:185], 0, s[6:7]
	v_lshl_add_u64 v[188:189], v[186:187], 0, s[6:7]
	v_lshl_add_u64 v[190:191], v[188:189], 0, s[6:7]
	s_mov_b64 s[6:7], 0x1000
	v_lshl_add_u64 v[232:233], v[140:141], 0, s[6:7]
	global_load_dwordx4 v[192:195], v[142:143], off
	global_load_dwordx4 v[196:199], v[178:179], off
	global_load_dwordx4 v[200:203], v[180:181], off
	global_load_dwordx4 v[204:207], v[182:183], off
	global_load_dwordx4 v[208:211], v[184:185], off
	global_load_dwordx4 v[212:215], v[186:187], off
	global_load_dwordx4 v[238:241], v[188:189], off
	global_load_dwordx4 v[242:245], v[190:191], off
	global_load_dwordx4 v[246:249], v[100:101], off
	global_load_dwordx4 v[148:151], v[142:143], off offset:1024
	global_load_dwordx4 v[152:155], v[178:179], off offset:1024
	global_load_dwordx4 v[156:159], v[180:181], off offset:1024
	global_load_dwordx4 v[160:163], v[182:183], off offset:1024
	global_load_dwordx4 v[164:167], v[184:185], off offset:1024
	global_load_dwordx4 v[168:171], v[186:187], off offset:1024
	global_load_dwordx4 v[172:175], v[188:189], off offset:1024
	global_load_dwordx4 v[250:253], v[190:191], off offset:1024
	global_load_dwordx4 v[228:231], v[100:101], off offset:1024
	s_waitcnt vmcnt(9)
	v_pk_add_f32 v[192:193], v[192:193], v[196:197]
	v_pk_add_f32 v[194:195], v[194:195], v[198:199]
	v_pk_add_f32 v[192:193], v[192:193], v[200:201]
	v_pk_add_f32 v[194:195], v[194:195], v[202:203]
	v_pk_add_f32 v[192:193], v[192:193], v[204:205]
	v_pk_add_f32 v[194:195], v[194:195], v[206:207]
	v_pk_add_f32 v[192:193], v[192:193], v[208:209]
	v_pk_add_f32 v[194:195], v[194:195], v[210:211]
	v_pk_add_f32 v[192:193], v[192:193], v[212:213]
	v_pk_add_f32 v[194:195], v[194:195], v[214:215]
	v_pk_add_f32 v[192:193], v[192:193], v[238:239]
	v_pk_add_f32 v[194:195], v[194:195], v[240:241]
	v_pk_add_f32 v[192:193], v[192:193], v[242:243]
	v_pk_add_f32 v[194:195], v[194:195], v[244:245]
	v_pk_fma_f32 v[92:93], v[192:193], v[246:247], v[92:93]
	v_pk_fma_f32 v[94:95], v[194:195], v[248:249], v[94:95]
	global_store_dwordx4 v[140:141], v[92:95], off
	s_waitcnt vmcnt(1)
	v_pk_add_f32 v[148:149], v[148:149], v[152:153]
	v_pk_add_f32 v[150:151], v[150:151], v[154:155]
	v_pk_add_f32 v[148:149], v[148:149], v[156:157]
	v_pk_add_f32 v[150:151], v[150:151], v[158:159]
	v_pk_add_f32 v[148:149], v[148:149], v[160:161]
	v_pk_add_f32 v[150:151], v[150:151], v[162:163]
	v_pk_add_f32 v[148:149], v[148:149], v[164:165]
	v_pk_add_f32 v[150:151], v[150:151], v[166:167]
	v_pk_add_f32 v[148:149], v[148:149], v[168:169]
	v_pk_add_f32 v[150:151], v[150:151], v[170:171]
	v_pk_add_f32 v[148:149], v[148:149], v[172:173]
	v_pk_add_f32 v[150:151], v[150:151], v[174:175]
	v_pk_add_f32 v[148:149], v[148:149], v[250:251]
	v_pk_add_f32 v[150:151], v[150:151], v[252:253]
	v_pk_fma_f32 v[88:89], v[148:149], v[228:229], v[88:89]
	v_pk_fma_f32 v[90:91], v[150:151], v[230:231], v[90:91]
	global_store_dwordx4 v[140:141], v[88:91], off offset:1024
	global_load_dwordx4 v[192:195], v[142:143], off offset:2048
	global_load_dwordx4 v[196:199], v[178:179], off offset:2048
	global_load_dwordx4 v[200:203], v[180:181], off offset:2048
	global_load_dwordx4 v[204:207], v[182:183], off offset:2048
	global_load_dwordx4 v[208:211], v[184:185], off offset:2048
	global_load_dwordx4 v[212:215], v[186:187], off offset:2048
	global_load_dwordx4 v[238:241], v[188:189], off offset:2048
	global_load_dwordx4 v[242:245], v[190:191], off offset:2048
	global_load_dwordx4 v[246:249], v[100:101], off offset:2048
	global_load_dwordx4 v[148:151], v[142:143], off offset:3072
	global_load_dwordx4 v[152:155], v[178:179], off offset:3072
	global_load_dwordx4 v[156:159], v[180:181], off offset:3072
	global_load_dwordx4 v[160:163], v[182:183], off offset:3072
	global_load_dwordx4 v[164:167], v[184:185], off offset:3072
	global_load_dwordx4 v[168:171], v[186:187], off offset:3072
	global_load_dwordx4 v[172:175], v[188:189], off offset:3072
	global_load_dwordx4 v[250:253], v[190:191], off offset:3072
	global_load_dwordx4 v[228:231], v[100:101], off offset:3072
	s_waitcnt vmcnt(9)
	v_pk_add_f32 v[192:193], v[192:193], v[196:197]
	v_pk_add_f32 v[194:195], v[194:195], v[198:199]
	v_pk_add_f32 v[192:193], v[192:193], v[200:201]
	v_pk_add_f32 v[194:195], v[194:195], v[202:203]
	v_pk_add_f32 v[192:193], v[192:193], v[204:205]
	v_pk_add_f32 v[194:195], v[194:195], v[206:207]
	v_pk_add_f32 v[192:193], v[192:193], v[208:209]
	v_pk_add_f32 v[194:195], v[194:195], v[210:211]
	v_pk_add_f32 v[192:193], v[192:193], v[212:213]
	v_pk_add_f32 v[194:195], v[194:195], v[214:215]
	v_pk_add_f32 v[192:193], v[192:193], v[238:239]
	v_pk_add_f32 v[194:195], v[194:195], v[240:241]
	v_pk_add_f32 v[192:193], v[192:193], v[242:243]
	v_pk_add_f32 v[194:195], v[194:195], v[244:245]
	v_pk_fma_f32 v[84:85], v[192:193], v[246:247], v[84:85]
	v_pk_fma_f32 v[86:87], v[194:195], v[248:249], v[86:87]
	global_store_dwordx4 v[140:141], v[84:87], off offset:2048
	s_waitcnt vmcnt(1)
; template <class T> DI T* LP(T* p) { asm volatile("" : "+s"(p)); return p; }
; #define PRM (*KP())
; DI void phase_norm(int l, int stage, bool skipctx, int fold, int gate_l, int gate_chunk, const void* latsrc, int lat_bf16) {
;     ...
;         if (isctx && fold) {
;             const float* part = (const float*)(LP(PRM.ws) + WS_PART) + ((size_t)b * CTXL + t) * DM; const float* gt = mod + ((size_t)gate_l * 3 + 2) * 12288 + (size_t)gate_chunk * DM;
;             float* xc = (float*)(LP(PRM.ws) + WS_XC) + ((size_t)b * CTXL + t) * DM;
; #pragma unroll
;             for (int j = 0; j < 8; ++j) { f32x4 a = *((const f32x4*)part + 64 * j + lane);
; #pragma unroll
;                 for (int k = 1; k < NSPLIT; ++k) a += *((const f32x4*)(part + (size_t)k * 512 * DM) + 64 * j + lane);
;                 v[j] += a * *((const f32x4*)gt + 64 * j + lane); *((f32x4*)xc + 64 * j + lane) = v[j]; }
;         }
	v_pk_add_f32 v[148:149], v[148:149], v[152:153]
	v_pk_add_f32 v[150:151], v[150:151], v[154:155]
	v_pk_add_f32 v[148:149], v[148:149], v[156:157]
	v_pk_add_f32 v[150:151], v[150:151], v[158:159]
	v_pk_add_f32 v[148:149], v[148:149], v[160:161]
	v_pk_add_f32 v[150:151], v[150:151], v[162:163]
	v_pk_add_f32 v[148:149], v[148:149], v[164:165]
	v_pk_add_f32 v[150:151], v[150:151], v[166:167]
	v_pk_add_f32 v[148:149], v[148:149], v[168:169]
	v_pk_add_f32 v[150:151], v[150:151], v[170:171]
	v_pk_add_f32 v[148:149], v[148:149], v[172:173]
	v_pk_add_f32 v[150:151], v[150:151], v[174:175]
	v_pk_add_f32 v[148:149], v[148:149], v[250:251]
	v_pk_add_f32 v[150:151], v[150:151], v[252:253]
	v_pk_fma_f32 v[80:81], v[148:149], v[228:229], v[80:81]
	v_pk_fma_f32 v[82:83], v[150:151], v[230:231], v[82:83]
	global_store_dwordx4 v[140:141], v[80:83], off offset:3072
	v_lshl_add_u64 v[142:143], v[142:143], 0, s[6:7]
	v_lshl_add_u64 v[178:179], v[178:179], 0, s[6:7]
	v_lshl_add_u64 v[180:181], v[180:181], 0, s[6:7]
	v_lshl_add_u64 v[182:183], v[182:183], 0, s[6:7]
	v_lshl_add_u64 v[184:185], v[184:185], 0, s[6:7]
	v_lshl_add_u64 v[186:187], v[186:187], 0, s[6:7]
	v_lshl_add_u64 v[188:189], v[188:189], 0, s[6:7]
	v_lshl_add_u64 v[190:191], v[190:191], 0, s[6:7]
	global_load_dwordx4 v[192:195], v[142:143], off
	global_load_dwordx4 v[196:199], v[178:179], off
	global_load_dwordx4 v[200:203], v[180:181], off
	global_load_dwordx4 v[204:207], v[182:183], off
	global_load_dwordx4 v[208:211], v[184:185], off
	global_load_dwordx4 v[212:215], v[186:187], off
	global_load_dwordx4 v[238:241], v[188:189], off
	global_load_dwordx4 v[242:245], v[190:191], off
	global_load_dwordx4 v[246:249], v[112:113], off
	global_load_dwordx4 v[148:151], v[142:143], off offset:1024
	global_load_dwordx4 v[152:155], v[178:179], off offset:1024
	global_load_dwordx4 v[156:159], v[180:181], off offset:1024
	global_load_dwordx4 v[160:163], v[182:183], off offset:1024
	global_load_dwordx4 v[164:167], v[184:185], off offset:1024
	global_load_dwordx4 v[168:171], v[186:187], off offset:1024
	global_load_dwordx4 v[172:175], v[188:189], off offset:1024
	global_load_dwordx4 v[250:253], v[190:191], off offset:1024
	global_load_dwordx4 v[228:231], v[114:115], off
	s_waitcnt vmcnt(9)
	v_pk_add_f32 v[192:193], v[192:193], v[196:197]
	v_pk_add_f32 v[194:195], v[194:195], v[198:199]
	v_pk_add_f32 v[192:193], v[192:193], v[200:201]
	v_pk_add_f32 v[194:195], v[194:195], v[202:203]
	v_pk_add_f32 v[192:193], v[192:193], v[204:205]
	v_pk_add_f32 v[194:195], v[194:195], v[206:207]
	v_pk_add_f32 v[192:193], v[192:193], v[208:209]
	v_pk_add_f32 v[194:195], v[194:195], v[210:211]
	v_pk_add_f32 v[192:193], v[192:193], v[212:213]
	v_pk_add_f32 v[194:195], v[194:195], v[214:215]
	v_pk_add_f32 v[192:193], v[192:193], v[238:239]
	v_pk_add_f32 v[194:195], v[194:195], v[240:241]
	v_pk_add_f32 v[192:193], v[192:193], v[242:243]
	v_pk_add_f32 v[194:195], v[194:195], v[244:245]
	v_pk_fma_f32 v[76:77], v[192:193], v[246:247], v[76:77]
	v_pk_fma_f32 v[78:79], v[194:195], v[248:249], v[78:79]
	global_store_dwordx4 v[232:233], v[76:79], off
	s_waitcnt vmcnt(1)
	v_pk_add_f32 v[148:149], v[148:149], v[152:153]
	v_pk_add_f32 v[150:151], v[150:151], v[154:155]
	v_pk_add_f32 v[148:149], v[148:149], v[156:157]
	v_pk_add_f32 v[150:151], v[150:151], v[158:159]
	v_pk_add_f32 v[148:149], v[148:149], v[160:161]
	v_pk_add_f32 v[150:151], v[150:151], v[162:163]
	v_pk_add_f32 v[148:149], v[148:149], v[164:165]
	v_pk_add_f32 v[150:151], v[150:151], v[166:167]
	v_pk_add_f32 v[148:149], v[148:149], v[168:169]
	v_pk_add_f32 v[150:151], v[150:151], v[170:171]
	v_pk_add_f32 v[148:149], v[148:149], v[172:173]
	v_pk_add_f32 v[150:151], v[150:151], v[174:175]
	v_pk_add_f32 v[148:149], v[148:149], v[250:251]
	v_pk_add_f32 v[150:151], v[150:151], v[252:253]
	v_pk_fma_f32 v[72:73], v[148:149], v[228:229], v[72:73]
	v_pk_fma_f32 v[74:75], v[150:151], v[230:231], v[74:75]
	global_store_dwordx4 v[232:233], v[72:75], off offset:1024
	global_load_dwordx4 v[192:195], v[142:143], off offset:2048
	global_load_dwordx4 v[196:199], v[178:179], off offset:2048
	global_load_dwordx4 v[200:203], v[180:181], off offset:2048
	global_load_dwordx4 v[204:207], v[182:183], off offset:2048
	global_load_dwordx4 v[208:211], v[184:185], off offset:2048
	global_load_dwordx4 v[212:215], v[186:187], off offset:2048
	global_load_dwordx4 v[238:241], v[188:189], off offset:2048
	global_load_dwordx4 v[242:245], v[190:191], off offset:2048
	global_load_dwordx4 v[246:249], v[116:117], off
	global_load_dwordx4 v[148:151], v[142:143], off offset:3072
	global_load_dwordx4 v[152:155], v[178:179], off offset:3072
	global_load_dwordx4 v[156:159], v[180:181], off offset:3072
	global_load_dwordx4 v[160:163], v[182:183], off offset:3072
	global_load_dwordx4 v[164:167], v[184:185], off offset:3072
	global_load_dwordx4 v[168:171], v[186:187], off offset:3072
	global_load_dwordx4 v[172:175], v[188:189], off offset:3072
	global_load_dwordx4 v[250:253], v[190:191], off offset:3072
	global_load_dwordx4 v[228:231], v[118:119], off
	s_waitcnt vmcnt(9)
	v_pk_add_f32 v[192:193], v[192:193], v[196:197]
	v_pk_add_f32 v[194:195], v[194:195], v[198:199]
	v_pk_add_f32 v[192:193], v[192:193], v[200:201]
	v_pk_add_f32 v[194:195], v[194:195], v[202:203]
	v_pk_add_f32 v[192:193], v[192:193], v[204:205]
	v_pk_add_f32 v[194:195], v[194:195], v[206:207]
	v_pk_add_f32 v[192:193], v[192:193], v[208:209]
	v_pk_add_f32 v[194:195], v[194:195], v[210:211]
	v_pk_add_f32 v[192:193], v[192:193], v[212:213]
	v_pk_add_f32 v[194:195], v[194:195], v[214:215]
	v_pk_add_f32 v[192:193], v[192:193], v[238:239]
	v_pk_add_f32 v[194:195], v[194:195], v[240:241]
	v_pk_add_f32 v[192:193], v[192:193], v[242:243]
	v_pk_add_f32 v[194:195], v[194:195], v[244:245]
	v_pk_fma_f32 v[68:69], v[192:193], v[246:247], v[68:69]
	v_pk_fma_f32 v[70:71], v[194:195], v[248:249], v[70:71]
	global_store_dwordx4 v[232:233], v[68:71], off offset:2048
	s_waitcnt vmcnt(1)
	v_pk_add_f32 v[148:149], v[148:149], v[152:153]
	v_pk_add_f32 v[150:151], v[150:151], v[154:155]
	v_pk_add_f32 v[148:149], v[148:149], v[156:157]
	v_pk_add_f32 v[150:151], v[150:151], v[158:159]
	v_pk_add_f32 v[148:149], v[148:149], v[160:161]
	v_pk_add_f32 v[150:151], v[150:151], v[162:163]
	v_pk_add_f32 v[148:149], v[148:149], v[164:165]
	v_pk_add_f32 v[150:151], v[150:151], v[166:167]
	v_pk_add_f32 v[148:149], v[148:149], v[168:169]
	v_pk_add_f32 v[150:151], v[150:151], v[170:171]
	v_pk_add_f32 v[148:149], v[148:149], v[172:173]
	v_pk_add_f32 v[150:151], v[150:151], v[174:175]
	v_pk_add_f32 v[148:149], v[148:149], v[250:251]
	v_pk_add_f32 v[150:151], v[150:151], v[252:253]
	v_pk_fma_f32 v[64:65], v[148:149], v[228:229], v[64:65]
	v_pk_fma_f32 v[66:67], v[150:151], v[230:231], v[66:67]
	global_store_dwordx4 v[232:233], v[64:67], off offset:3072
	s_branch .LBB0_838
